# v6 + s_setprio removed from the MB=3 K-loops of P5/P6/P9 as well
# baseline (speedup 1.0000x reference)
.LBB0_828:
	s_barrier
	v_mfma_f32_16x16x32_bf16 v[24:27], v[100:103], v[148:151], v[24:27]
	v_mfma_f32_16x16x32_bf16 v[20:23], v[108:111], v[148:151], v[20:23]
	v_mfma_f32_16x16x32_bf16 v[16:19], v[100:103], v[140:143], v[16:19]
	v_mfma_f32_16x16x32_bf16 v[12:15], v[108:111], v[140:143], v[12:15]
	v_mfma_f32_16x16x32_bf16 v[6:9], v[100:103], v[132:135], v[8:11]
	v_mfma_f32_16x16x32_bf16 v[2:5], v[108:111], v[132:135], v[2:5]
	v_mfma_f32_16x16x32_bf16 v[24:27], v[104:107], v[152:155], v[24:27]
	v_mfma_f32_16x16x32_bf16 v[20:23], v[112:115], v[152:155], v[20:23]
	v_mfma_f32_16x16x32_bf16 v[16:19], v[104:107], v[144:147], v[16:19]
	v_mfma_f32_16x16x32_bf16 v[12:15], v[112:115], v[144:147], v[12:15]
	v_mfma_f32_16x16x32_bf16 v[8:11], v[104:107], v[136:139], v[6:9]
	v_mfma_f32_16x16x32_bf16 v[4:7], v[112:115], v[136:139], v[2:5]
	s_add_i32 s65, s65, 2
	s_add_u32 s46, s46, 0x100
	s_addc_u32 s47, s47, 0
	s_add_u32 s34, s34, 0x100
	s_addc_u32 s35, s35, 0
	s_cmp_gt_u32 s65, 29
	s_barrier
	s_cbranch_scc1 .LBB0_845

.LBB0_831:
	s_add_u32 s30, s46, 0xfff40080
	s_addc_u32 s31, s47, -1
	s_waitcnt lgkmcnt(8)
	s_barrier
	s_waitcnt lgkmcnt(0)
	s_cmp_eq_u32 s65, 28
	s_cselect_b32 s49, s25, s31
	s_cselect_b32 s48, s24, s30
	s_cselect_b32 s31, s7, s35
	s_cselect_b32 s30, s23, s34
	s_waitcnt lgkmcnt(0)
	v_mfma_f32_16x16x32_bf16 v[96:99], v[100:103], v[148:151], v[96:99]
	v_mfma_f32_16x16x32_bf16 v[92:95], v[108:111], v[148:151], v[92:95]
	v_mfma_f32_16x16x32_bf16 v[88:91], v[100:103], v[140:143], v[88:91]
	v_mfma_f32_16x16x32_bf16 v[84:87], v[108:111], v[140:143], v[84:87]
	v_mfma_f32_16x16x32_bf16 v[80:83], v[100:103], v[132:135], v[80:83]
	v_mfma_f32_16x16x32_bf16 v[76:79], v[108:111], v[132:135], v[76:79]
	v_mfma_f32_16x16x32_bf16 v[96:99], v[104:107], v[152:155], v[96:99]
	v_mfma_f32_16x16x32_bf16 v[92:95], v[112:115], v[152:155], v[92:95]
	v_mfma_f32_16x16x32_bf16 v[88:91], v[104:107], v[144:147], v[88:91]
	v_mfma_f32_16x16x32_bf16 v[84:87], v[112:115], v[144:147], v[84:87]
	v_mfma_f32_16x16x32_bf16 v[80:83], v[104:107], v[136:139], v[80:83]
	v_mfma_f32_16x16x32_bf16 v[76:79], v[112:115], v[136:139], v[76:79]
	s_barrier
	s_mov_b32 m0, s41
	v_add_u32_e32 v1, 0x14000, v187
	v_lshl_add_u64 v[174:175], s[30:31], 0, v[158:159]
	ds_read_b128 v[116:119], v1
	ds_read_b128 v[120:123], v1 offset:1024
	ds_read_b128 v[124:127], v1 offset:2048
	ds_read_b128 v[128:131], v1 offset:3072
	global_load_lds_dwordx4 v[174:175], off
	v_lshl_add_u64 v[176:177], s[30:31], 0, v[160:161]
	s_mov_b32 m0, s52
	s_nop 0
	global_load_lds_dwordx4 v[176:177], off
	s_barrier
	s_waitcnt lgkmcnt(0)
	s_waitcnt lgkmcnt(0)
	v_mfma_f32_16x16x32_bf16 v[72:75], v[116:119], v[148:151], v[72:75]
	v_mfma_f32_16x16x32_bf16 v[68:71], v[124:127], v[148:151], v[68:71]
	v_mfma_f32_16x16x32_bf16 v[64:67], v[116:119], v[140:143], v[64:67]
	v_mfma_f32_16x16x32_bf16 v[60:63], v[124:127], v[140:143], v[60:63]
	v_mfma_f32_16x16x32_bf16 v[56:59], v[116:119], v[132:135], v[56:59]
	v_mfma_f32_16x16x32_bf16 v[52:55], v[124:127], v[132:135], v[52:55]
	v_mfma_f32_16x16x32_bf16 v[72:75], v[120:123], v[152:155], v[72:75]
	v_mfma_f32_16x16x32_bf16 v[68:71], v[128:131], v[152:155], v[68:71]
	v_mfma_f32_16x16x32_bf16 v[64:67], v[120:123], v[144:147], v[64:67]
	v_mfma_f32_16x16x32_bf16 v[60:63], v[128:131], v[144:147], v[60:63]
	v_mfma_f32_16x16x32_bf16 v[56:59], v[120:123], v[136:139], v[56:59]
	v_mfma_f32_16x16x32_bf16 v[52:55], v[128:131], v[136:139], v[52:55]
	s_mov_b32 m0, s40
	v_lshl_add_u64 v[178:179], s[48:49], 0, v[156:157]
	s_barrier
	ds_read_b128 v[148:151], v188 offset:16384
	ds_read_b128 v[152:155], v188 offset:17408
	ds_read_b128 v[140:143], v188 offset:18432
	ds_read_b128 v[144:147], v188 offset:19456
	ds_read_b128 v[132:135], v188 offset:20480
	ds_read_b128 v[136:139], v188 offset:21504
	global_load_lds_dwordx4 v[178:179], off
	s_and_b64 vcc, exec, s[4:5]
	v_lshl_add_u64 v[172:173], s[48:49], 0, v[162:163]
	s_cbranch_vccnz .LBB0_833
	s_add_i32 m0, s40, 0x2000
	s_nop 0
	global_load_lds_dwordx4 v[172:173], off
.LBB0_833:
	s_barrier
	s_waitcnt lgkmcnt(0)
	s_waitcnt lgkmcnt(0)
	v_mfma_f32_16x16x32_bf16 v[48:51], v[100:103], v[148:151], v[48:51]
	v_mfma_f32_16x16x32_bf16 v[44:47], v[108:111], v[148:151], v[44:47]
	v_mfma_f32_16x16x32_bf16 v[40:43], v[100:103], v[140:143], v[40:43]
	v_mfma_f32_16x16x32_bf16 v[36:39], v[108:111], v[140:143], v[36:39]
	v_mfma_f32_16x16x32_bf16 v[32:35], v[100:103], v[132:135], v[32:35]
	v_mfma_f32_16x16x32_bf16 v[28:31], v[108:111], v[132:135], v[28:31]
	v_mfma_f32_16x16x32_bf16 v[48:51], v[104:107], v[152:155], v[48:51]
	v_mfma_f32_16x16x32_bf16 v[44:47], v[112:115], v[152:155], v[44:47]
	v_mfma_f32_16x16x32_bf16 v[40:43], v[104:107], v[144:147], v[40:43]
	v_mfma_f32_16x16x32_bf16 v[36:39], v[112:115], v[144:147], v[36:39]
	v_mfma_f32_16x16x32_bf16 v[32:35], v[104:107], v[136:139], v[32:35]
	v_mfma_f32_16x16x32_bf16 v[28:31], v[112:115], v[136:139], v[28:31]
	s_barrier
	s_add_u32 s50, s30, 0x100000
	s_addc_u32 s51, s31, 0
	s_mov_b32 m0, s53
	v_lshl_add_u64 v[2:3], s[50:51], 0, v[158:159]
	global_load_lds_dwordx4 v[2:3], off
	v_lshl_add_u64 v[2:3], s[50:51], 0, v[160:161]
	s_mov_b32 m0, s54
	s_mov_b64 s[50:51], -1
	global_load_lds_dwordx4 v[2:3], off
	s_and_b64 vcc, exec, s[10:11]
	s_cbranch_vccz .LBB0_835
	s_waitcnt vmcnt(6)
	s_mov_b64 s[50:51], 0

.LBB0_837:
	s_barrier
	v_mfma_f32_16x16x32_bf16 v[24:27], v[116:119], v[148:151], v[24:27]
	v_mfma_f32_16x16x32_bf16 v[20:23], v[124:127], v[148:151], v[20:23]
	v_mfma_f32_16x16x32_bf16 v[16:19], v[116:119], v[140:143], v[16:19]
	v_mfma_f32_16x16x32_bf16 v[12:15], v[124:127], v[140:143], v[12:15]
	v_mfma_f32_16x16x32_bf16 v[8:11], v[116:119], v[132:135], v[8:11]
	v_mfma_f32_16x16x32_bf16 v[2:5], v[124:127], v[132:135], v[4:7]
	v_mfma_f32_16x16x32_bf16 v[24:27], v[120:123], v[152:155], v[24:27]
	v_mfma_f32_16x16x32_bf16 v[20:23], v[128:131], v[152:155], v[20:23]
	v_mfma_f32_16x16x32_bf16 v[16:19], v[120:123], v[144:147], v[16:19]
	v_mfma_f32_16x16x32_bf16 v[12:15], v[128:131], v[144:147], v[12:15]
	v_mfma_f32_16x16x32_bf16 v[8:11], v[120:123], v[136:139], v[8:11]
	v_mfma_f32_16x16x32_bf16 v[2:5], v[128:131], v[136:139], v[2:5]
	v_add_u32_e32 v1, 0x18000, v187
	s_barrier
	ds_read_b128 v[116:119], v1
	ds_read_b128 v[120:123], v1 offset:1024
	ds_read_b128 v[124:127], v1 offset:2048
	ds_read_b128 v[128:131], v1 offset:3072
	s_add_u32 s48, s48, 0xc0000
	s_addc_u32 s49, s49, 0
	s_mov_b32 m0, s55
	v_lshl_add_u64 v[6:7], s[48:49], 0, v[156:157]
	ds_read_b128 v[148:151], v188 offset:32768
	ds_read_b128 v[152:155], v188 offset:33792
	ds_read_b128 v[140:143], v188 offset:34816
	ds_read_b128 v[144:147], v188 offset:35840
	ds_read_b128 v[132:135], v188 offset:36864
	ds_read_b128 v[136:139], v188 offset:37888
	global_load_lds_dwordx4 v[6:7], off
	s_and_b64 vcc, exec, s[4:5]
	s_cbranch_vccnz .LBB0_839
	v_lshl_add_u64 v[6:7], s[48:49], 0, v[162:163]
	s_add_i32 m0, s40, 0x6000
	s_nop 0
	global_load_lds_dwordx4 v[6:7], off
.LBB0_839:
	s_waitcnt lgkmcnt(8)
	s_barrier
	s_waitcnt lgkmcnt(0)
	s_waitcnt lgkmcnt(0)
	v_mfma_f32_16x16x32_bf16 v[96:99], v[116:119], v[148:151], v[96:99]
	v_mfma_f32_16x16x32_bf16 v[92:95], v[124:127], v[148:151], v[92:95]
	v_mfma_f32_16x16x32_bf16 v[88:91], v[116:119], v[140:143], v[88:91]
	v_mfma_f32_16x16x32_bf16 v[84:87], v[124:127], v[140:143], v[84:87]
	v_mfma_f32_16x16x32_bf16 v[80:83], v[116:119], v[132:135], v[80:83]
	v_mfma_f32_16x16x32_bf16 v[76:79], v[124:127], v[132:135], v[76:79]
	v_mfma_f32_16x16x32_bf16 v[96:99], v[120:123], v[152:155], v[96:99]
	v_mfma_f32_16x16x32_bf16 v[92:95], v[128:131], v[152:155], v[92:95]
	v_mfma_f32_16x16x32_bf16 v[88:91], v[120:123], v[144:147], v[88:91]
	v_mfma_f32_16x16x32_bf16 v[84:87], v[128:131], v[144:147], v[84:87]
	v_mfma_f32_16x16x32_bf16 v[80:83], v[120:123], v[136:139], v[80:83]
	v_mfma_f32_16x16x32_bf16 v[76:79], v[128:131], v[136:139], v[76:79]
	s_barrier
	s_mov_b32 m0, s56
	v_add_u32_e32 v1, 0x1c000, v187
	v_lshl_add_u64 v[6:7], v[174:175], 0, s[20:21]
	ds_read_b128 v[100:103], v1
	ds_read_b128 v[104:107], v1 offset:1024
	ds_read_b128 v[108:111], v1 offset:2048
	ds_read_b128 v[112:115], v1 offset:3072
	global_load_lds_dwordx4 v[6:7], off
	v_lshl_add_u64 v[6:7], v[176:177], 0, s[20:21]
	s_mov_b32 m0, s57
	s_nop 0
	global_load_lds_dwordx4 v[6:7], off
	s_barrier
	s_waitcnt lgkmcnt(0)
	s_waitcnt lgkmcnt(0)
	v_mfma_f32_16x16x32_bf16 v[72:75], v[100:103], v[148:151], v[72:75]
	v_mfma_f32_16x16x32_bf16 v[68:71], v[108:111], v[148:151], v[68:71]
	v_mfma_f32_16x16x32_bf16 v[64:67], v[100:103], v[140:143], v[64:67]
	v_mfma_f32_16x16x32_bf16 v[60:63], v[108:111], v[140:143], v[60:63]
	v_mfma_f32_16x16x32_bf16 v[56:59], v[100:103], v[132:135], v[56:59]
	v_mfma_f32_16x16x32_bf16 v[52:55], v[108:111], v[132:135], v[52:55]
	v_mfma_f32_16x16x32_bf16 v[72:75], v[104:107], v[152:155], v[72:75]
	v_mfma_f32_16x16x32_bf16 v[68:71], v[112:115], v[152:155], v[68:71]
	v_mfma_f32_16x16x32_bf16 v[64:67], v[104:107], v[144:147], v[64:67]
	v_mfma_f32_16x16x32_bf16 v[60:63], v[112:115], v[144:147], v[60:63]
	v_mfma_f32_16x16x32_bf16 v[56:59], v[104:107], v[136:139], v[56:59]
	v_mfma_f32_16x16x32_bf16 v[52:55], v[112:115], v[136:139], v[52:55]
	s_mov_b32 m0, s58
	v_lshl_add_u64 v[6:7], v[178:179], 0, s[20:21]
	s_barrier
	ds_read_b128 v[148:151], v188 offset:49152
	ds_read_b128 v[152:155], v188 offset:50176
	ds_read_b128 v[140:143], v188 offset:51200
	ds_read_b128 v[144:147], v188 offset:52224
	ds_read_b128 v[132:135], v188 offset:53248
	ds_read_b128 v[136:139], v188 offset:54272
	global_load_lds_dwordx4 v[6:7], off
	s_and_b64 vcc, exec, s[4:5]
	s_cbranch_vccnz .LBB0_841
	v_lshl_add_u64 v[6:7], v[172:173], 0, s[20:21]
	s_add_i32 m0, s40, 0xa000
	s_nop 0
	global_load_lds_dwordx4 v[6:7], off
.LBB0_841:
	s_barrier
	s_waitcnt lgkmcnt(0)
	s_waitcnt lgkmcnt(0)
	v_mfma_f32_16x16x32_bf16 v[48:51], v[116:119], v[148:151], v[48:51]
	v_mfma_f32_16x16x32_bf16 v[44:47], v[124:127], v[148:151], v[44:47]
	v_mfma_f32_16x16x32_bf16 v[40:43], v[116:119], v[140:143], v[40:43]
	v_mfma_f32_16x16x32_bf16 v[36:39], v[124:127], v[140:143], v[36:39]
	v_mfma_f32_16x16x32_bf16 v[32:35], v[116:119], v[132:135], v[32:35]
	v_mfma_f32_16x16x32_bf16 v[28:31], v[124:127], v[132:135], v[28:31]
	v_mfma_f32_16x16x32_bf16 v[48:51], v[120:123], v[152:155], v[48:51]
	v_mfma_f32_16x16x32_bf16 v[44:47], v[128:131], v[152:155], v[44:47]
	v_mfma_f32_16x16x32_bf16 v[40:43], v[120:123], v[144:147], v[40:43]
	v_mfma_f32_16x16x32_bf16 v[36:39], v[128:131], v[144:147], v[36:39]
	v_mfma_f32_16x16x32_bf16 v[32:35], v[120:123], v[136:139], v[32:35]
	v_mfma_f32_16x16x32_bf16 v[28:31], v[128:131], v[136:139], v[28:31]
	s_barrier
	s_add_u32 s30, s30, 0x100080
	s_addc_u32 s31, s31, 0
	s_mov_b32 m0, s59
	v_lshl_add_u64 v[6:7], s[30:31], 0, v[158:159]
	global_load_lds_dwordx4 v[6:7], off
	v_lshl_add_u64 v[6:7], s[30:31], 0, v[160:161]
	s_mov_b32 m0, s60
	s_mov_b64 s[30:31], -1
	global_load_lds_dwordx4 v[6:7], off
	s_and_b64 vcc, exec, s[10:11]
	s_cbranch_vccz .LBB0_843
	s_waitcnt vmcnt(6)
	s_mov_b64 s[30:31], 0

.LBB0_924:
	s_barrier
	v_mfma_f32_16x16x32_bf16 v[40:43], v[96:99], v[144:147], v[40:43]
	v_mfma_f32_16x16x32_bf16 v[20:23], v[104:107], v[144:147], v[20:23]
	v_mfma_f32_16x16x32_bf16 v[24:27], v[96:99], v[136:139], v[24:27]
	v_mfma_f32_16x16x32_bf16 v[16:19], v[104:107], v[136:139], v[16:19]
	v_mfma_f32_16x16x32_bf16 v[4:7], v[96:99], v[128:131], v[4:7]
	v_mfma_f32_16x16x32_bf16 v[0:3], v[104:107], v[128:131], v[0:3]
	v_mfma_f32_16x16x32_bf16 v[40:43], v[100:103], v[148:151], v[40:43]
	v_mfma_f32_16x16x32_bf16 v[20:23], v[108:111], v[148:151], v[20:23]
	v_mfma_f32_16x16x32_bf16 v[24:27], v[100:103], v[140:143], v[24:27]
	v_mfma_f32_16x16x32_bf16 v[16:19], v[108:111], v[140:143], v[16:19]
	v_mfma_f32_16x16x32_bf16 v[4:7], v[100:103], v[132:135], v[4:7]
	v_mfma_f32_16x16x32_bf16 v[0:3], v[108:111], v[132:135], v[0:3]
	s_add_i32 s82, s82, 2
	s_add_u32 s8, s8, 0x100
	s_addc_u32 s9, s9, 0
	s_add_u32 s52, s52, 0x100
	s_addc_u32 s53, s53, 0
	s_cmp_gt_u32 s82, 29
	s_barrier
	s_cbranch_scc1 .LBB0_941

.LBB0_927:
	s_add_u32 s34, s8, 0xfffa0080
	s_addc_u32 s35, s9, -1
	s_waitcnt lgkmcnt(8)
	s_barrier
	s_waitcnt lgkmcnt(0)
	s_cmp_eq_u32 s82, 28
	s_cselect_b32 s57, s49, s35
	s_cselect_b32 s56, s48, s34
	s_cselect_b32 s55, s17, s53
	s_cselect_b32 s54, s16, s52
	s_waitcnt lgkmcnt(0)
	v_mfma_f32_16x16x32_bf16 v[88:91], v[96:99], v[144:147], v[88:91]
	v_mfma_f32_16x16x32_bf16 v[92:95], v[104:107], v[144:147], v[92:95]
	v_mfma_f32_16x16x32_bf16 v[76:79], v[96:99], v[136:139], v[76:79]
	v_mfma_f32_16x16x32_bf16 v[80:83], v[104:107], v[136:139], v[80:83]
	v_mfma_f32_16x16x32_bf16 v[60:63], v[96:99], v[128:131], v[60:63]
	v_mfma_f32_16x16x32_bf16 v[64:67], v[104:107], v[128:131], v[64:67]
	v_mfma_f32_16x16x32_bf16 v[88:91], v[100:103], v[148:151], v[88:91]
	v_mfma_f32_16x16x32_bf16 v[92:95], v[108:111], v[148:151], v[92:95]
	v_mfma_f32_16x16x32_bf16 v[76:79], v[100:103], v[140:143], v[76:79]
	v_mfma_f32_16x16x32_bf16 v[80:83], v[108:111], v[140:143], v[80:83]
	v_mfma_f32_16x16x32_bf16 v[60:63], v[100:103], v[132:135], v[60:63]
	v_mfma_f32_16x16x32_bf16 v[64:67], v[108:111], v[132:135], v[64:67]
	s_barrier
	s_mov_b32 m0, s40
	v_add_u32_e32 v124, 0x14000, v194
	v_lshl_add_u64 v[172:173], s[54:55], 0, v[152:153]
	ds_read_b128 v[112:115], v124
	ds_read_b128 v[116:119], v124 offset:1024
	ds_read_b128 v[120:123], v124 offset:2048
	ds_read_b128 v[124:127], v124 offset:3072
	global_load_lds_dwordx4 v[172:173], off
	v_lshl_add_u64 v[174:175], s[54:55], 0, v[154:155]
	s_mov_b32 m0, s41
	s_nop 0
	global_load_lds_dwordx4 v[174:175], off
	s_barrier
	s_waitcnt lgkmcnt(0)
	s_waitcnt lgkmcnt(0)
	v_mfma_f32_16x16x32_bf16 v[84:87], v[112:115], v[144:147], v[84:87]
	v_mfma_f32_16x16x32_bf16 v[68:71], v[120:123], v[144:147], v[68:71]
	v_mfma_f32_16x16x32_bf16 v[72:75], v[112:115], v[136:139], v[72:75]
	v_mfma_f32_16x16x32_bf16 v[52:55], v[120:123], v[136:139], v[52:55]
	v_mfma_f32_16x16x32_bf16 v[56:59], v[112:115], v[128:131], v[56:59]
	v_mfma_f32_16x16x32_bf16 v[36:39], v[120:123], v[128:131], v[36:39]
	v_mfma_f32_16x16x32_bf16 v[84:87], v[116:119], v[148:151], v[84:87]
	v_mfma_f32_16x16x32_bf16 v[68:71], v[124:127], v[148:151], v[68:71]
	v_mfma_f32_16x16x32_bf16 v[72:75], v[116:119], v[140:143], v[72:75]
	v_mfma_f32_16x16x32_bf16 v[52:55], v[124:127], v[140:143], v[52:55]
	v_mfma_f32_16x16x32_bf16 v[56:59], v[116:119], v[132:135], v[56:59]
	v_mfma_f32_16x16x32_bf16 v[36:39], v[124:127], v[132:135], v[36:39]
	s_mov_b32 m0, s39
	v_lshl_add_u64 v[176:177], s[56:57], 0, v[152:153]
	s_barrier
	ds_read_b128 v[144:147], v196 offset:16384
	ds_read_b128 v[148:151], v196 offset:17408
	ds_read_b128 v[136:139], v196 offset:18432
	ds_read_b128 v[140:143], v196 offset:19456
	ds_read_b128 v[128:131], v196 offset:20480
	ds_read_b128 v[132:135], v196 offset:21504
	global_load_lds_dwordx4 v[176:177], off
	s_and_b64 vcc, exec, s[4:5]
	v_lshl_add_u64 v[170:171], s[56:57], 0, v[154:155]
	s_cbranch_vccnz .LBB0_929
	s_add_i32 m0, s39, 0x2000
	s_nop 0
	global_load_lds_dwordx4 v[170:171], off
.LBB0_929:
	s_barrier
	s_waitcnt lgkmcnt(0)
	s_waitcnt lgkmcnt(0)
	v_mfma_f32_16x16x32_bf16 v[44:47], v[96:99], v[144:147], v[44:47]
	v_mfma_f32_16x16x32_bf16 v[48:51], v[104:107], v[144:147], v[48:51]
	v_mfma_f32_16x16x32_bf16 v[28:31], v[96:99], v[136:139], v[28:31]
	v_mfma_f32_16x16x32_bf16 v[32:35], v[104:107], v[136:139], v[32:35]
	v_mfma_f32_16x16x32_bf16 v[12:15], v[96:99], v[128:131], v[12:15]
	v_mfma_f32_16x16x32_bf16 v[8:11], v[104:107], v[128:131], v[8:11]
	v_mfma_f32_16x16x32_bf16 v[44:47], v[100:103], v[148:151], v[44:47]
	v_mfma_f32_16x16x32_bf16 v[48:51], v[108:111], v[148:151], v[48:51]
	v_mfma_f32_16x16x32_bf16 v[28:31], v[100:103], v[140:143], v[28:31]
	v_mfma_f32_16x16x32_bf16 v[32:35], v[108:111], v[140:143], v[32:35]
	v_mfma_f32_16x16x32_bf16 v[12:15], v[100:103], v[132:135], v[12:15]
	v_mfma_f32_16x16x32_bf16 v[8:11], v[108:111], v[132:135], v[8:11]
	s_barrier
	s_add_u32 s34, s54, 0x80000
	s_addc_u32 s35, s55, 0
	s_mov_b32 m0, s60
	v_lshl_add_u64 v[96:97], s[34:35], 0, v[152:153]
	global_load_lds_dwordx4 v[96:97], off
	v_lshl_add_u64 v[96:97], s[34:35], 0, v[154:155]
	s_mov_b32 m0, s61
	s_mov_b64 s[58:59], -1
	global_load_lds_dwordx4 v[96:97], off
	s_and_b64 vcc, exec, s[18:19]
	s_cbranch_vccz .LBB0_931
	s_waitcnt vmcnt(6)
	s_mov_b64 s[58:59], 0

.LBB0_933:
	s_barrier
	v_mfma_f32_16x16x32_bf16 v[40:43], v[112:115], v[144:147], v[40:43]
	v_mfma_f32_16x16x32_bf16 v[20:23], v[120:123], v[144:147], v[20:23]
	v_mfma_f32_16x16x32_bf16 v[24:27], v[112:115], v[136:139], v[24:27]
	v_mfma_f32_16x16x32_bf16 v[16:19], v[120:123], v[136:139], v[16:19]
	v_mfma_f32_16x16x32_bf16 v[4:7], v[112:115], v[128:131], v[4:7]
	v_mfma_f32_16x16x32_bf16 v[0:3], v[120:123], v[128:131], v[0:3]
	v_mfma_f32_16x16x32_bf16 v[40:43], v[116:119], v[148:151], v[40:43]
	v_mfma_f32_16x16x32_bf16 v[20:23], v[124:127], v[148:151], v[20:23]
	v_mfma_f32_16x16x32_bf16 v[24:27], v[116:119], v[140:143], v[24:27]
	v_mfma_f32_16x16x32_bf16 v[16:19], v[124:127], v[140:143], v[16:19]
	v_mfma_f32_16x16x32_bf16 v[4:7], v[116:119], v[132:135], v[4:7]
	v_mfma_f32_16x16x32_bf16 v[0:3], v[124:127], v[132:135], v[0:3]
	v_add_u32_e32 v96, 0x18000, v194
	s_barrier
	ds_read_b128 v[112:115], v96
	ds_read_b128 v[116:119], v96 offset:1024
	ds_read_b128 v[120:123], v96 offset:2048
	ds_read_b128 v[124:127], v96 offset:3072
	s_add_u32 s56, s56, 0x60000
	s_addc_u32 s57, s57, 0
	s_mov_b32 m0, s62
	v_lshl_add_u64 v[96:97], s[56:57], 0, v[152:153]
	ds_read_b128 v[144:147], v196 offset:32768
	ds_read_b128 v[148:151], v196 offset:33792
	ds_read_b128 v[136:139], v196 offset:34816
	ds_read_b128 v[140:143], v196 offset:35840
	ds_read_b128 v[128:131], v196 offset:36864
	ds_read_b128 v[132:135], v196 offset:37888
	global_load_lds_dwordx4 v[96:97], off
	s_and_b64 vcc, exec, s[4:5]
	s_cbranch_vccnz .LBB0_935
	v_lshl_add_u64 v[96:97], s[56:57], 0, v[154:155]
	s_add_i32 m0, s39, 0x6000
	s_nop 0
	global_load_lds_dwordx4 v[96:97], off
.LBB0_935:
	s_waitcnt lgkmcnt(8)
	s_barrier
	s_waitcnt lgkmcnt(0)
	s_waitcnt lgkmcnt(0)
	v_mfma_f32_16x16x32_bf16 v[88:91], v[112:115], v[144:147], v[88:91]
	v_mfma_f32_16x16x32_bf16 v[92:95], v[120:123], v[144:147], v[92:95]
	v_mfma_f32_16x16x32_bf16 v[76:79], v[112:115], v[136:139], v[76:79]
	v_mfma_f32_16x16x32_bf16 v[80:83], v[120:123], v[136:139], v[80:83]
	v_mfma_f32_16x16x32_bf16 v[60:63], v[112:115], v[128:131], v[60:63]
	v_mfma_f32_16x16x32_bf16 v[64:67], v[120:123], v[128:131], v[64:67]
	v_mfma_f32_16x16x32_bf16 v[88:91], v[116:119], v[148:151], v[88:91]
	v_mfma_f32_16x16x32_bf16 v[92:95], v[124:127], v[148:151], v[92:95]
	v_mfma_f32_16x16x32_bf16 v[76:79], v[116:119], v[140:143], v[76:79]
	v_mfma_f32_16x16x32_bf16 v[80:83], v[124:127], v[140:143], v[80:83]
	v_mfma_f32_16x16x32_bf16 v[60:63], v[116:119], v[132:135], v[60:63]
	v_mfma_f32_16x16x32_bf16 v[64:67], v[124:127], v[132:135], v[64:67]
	s_barrier
	s_mov_b32 m0, s63
	v_add_u32_e32 v108, 0x1c000, v194
	v_lshl_add_u64 v[172:173], v[172:173], 0, s[30:31]
	ds_read_b128 v[96:99], v108
	ds_read_b128 v[100:103], v108 offset:1024
	ds_read_b128 v[104:107], v108 offset:2048
	ds_read_b128 v[108:111], v108 offset:3072
	global_load_lds_dwordx4 v[172:173], off
	v_lshl_add_u64 v[172:173], v[174:175], 0, s[30:31]
	s_mov_b32 m0, s64
	s_nop 0
	global_load_lds_dwordx4 v[172:173], off
	s_barrier
	s_waitcnt lgkmcnt(0)
	s_waitcnt lgkmcnt(0)
	v_mfma_f32_16x16x32_bf16 v[84:87], v[96:99], v[144:147], v[84:87]
	v_mfma_f32_16x16x32_bf16 v[68:71], v[104:107], v[144:147], v[68:71]
	v_mfma_f32_16x16x32_bf16 v[72:75], v[96:99], v[136:139], v[72:75]
	v_mfma_f32_16x16x32_bf16 v[52:55], v[104:107], v[136:139], v[52:55]
	v_mfma_f32_16x16x32_bf16 v[56:59], v[96:99], v[128:131], v[56:59]
	v_mfma_f32_16x16x32_bf16 v[36:39], v[104:107], v[128:131], v[36:39]
	v_mfma_f32_16x16x32_bf16 v[84:87], v[100:103], v[148:151], v[84:87]
	v_mfma_f32_16x16x32_bf16 v[68:71], v[108:111], v[148:151], v[68:71]
	v_mfma_f32_16x16x32_bf16 v[72:75], v[100:103], v[140:143], v[72:75]
	v_mfma_f32_16x16x32_bf16 v[52:55], v[108:111], v[140:143], v[52:55]
	v_mfma_f32_16x16x32_bf16 v[56:59], v[100:103], v[132:135], v[56:59]
	v_mfma_f32_16x16x32_bf16 v[36:39], v[108:111], v[132:135], v[36:39]
	s_mov_b32 m0, s65
	v_lshl_add_u64 v[172:173], v[176:177], 0, s[30:31]
	s_barrier
	ds_read_b128 v[144:147], v196 offset:49152
	ds_read_b128 v[148:151], v196 offset:50176
	ds_read_b128 v[136:139], v196 offset:51200
	ds_read_b128 v[140:143], v196 offset:52224
	ds_read_b128 v[128:131], v196 offset:53248
	ds_read_b128 v[132:135], v196 offset:54272
	global_load_lds_dwordx4 v[172:173], off
	s_and_b64 vcc, exec, s[4:5]
	s_cbranch_vccnz .LBB0_937
	v_lshl_add_u64 v[170:171], v[170:171], 0, s[30:31]
	s_add_i32 m0, s39, 0xa000
	s_nop 0
	global_load_lds_dwordx4 v[170:171], off
.LBB0_937:
	s_barrier
	s_waitcnt lgkmcnt(0)
	s_waitcnt lgkmcnt(0)
	v_mfma_f32_16x16x32_bf16 v[44:47], v[112:115], v[144:147], v[44:47]
	v_mfma_f32_16x16x32_bf16 v[48:51], v[120:123], v[144:147], v[48:51]
	v_mfma_f32_16x16x32_bf16 v[28:31], v[112:115], v[136:139], v[28:31]
	v_mfma_f32_16x16x32_bf16 v[32:35], v[120:123], v[136:139], v[32:35]
	v_mfma_f32_16x16x32_bf16 v[12:15], v[112:115], v[128:131], v[12:15]
	v_mfma_f32_16x16x32_bf16 v[8:11], v[120:123], v[128:131], v[8:11]
	v_mfma_f32_16x16x32_bf16 v[44:47], v[116:119], v[148:151], v[44:47]
	v_mfma_f32_16x16x32_bf16 v[48:51], v[124:127], v[148:151], v[48:51]
	v_mfma_f32_16x16x32_bf16 v[28:31], v[116:119], v[140:143], v[28:31]
	v_mfma_f32_16x16x32_bf16 v[32:35], v[124:127], v[140:143], v[32:35]
	v_mfma_f32_16x16x32_bf16 v[12:15], v[116:119], v[132:135], v[12:15]
	v_mfma_f32_16x16x32_bf16 v[8:11], v[124:127], v[132:135], v[8:11]
	s_barrier
	s_add_u32 s34, s54, 0x80080
	s_addc_u32 s35, s55, 0
	s_mov_b32 m0, s66
	v_lshl_add_u64 v[112:113], s[34:35], 0, v[152:153]
	global_load_lds_dwordx4 v[112:113], off
	v_lshl_add_u64 v[112:113], s[34:35], 0, v[154:155]
	s_mov_b32 m0, s67
	s_mov_b64 s[54:55], -1
	global_load_lds_dwordx4 v[112:113], off
	s_and_b64 vcc, exec, s[18:19]
	s_cbranch_vccz .LBB0_939
	s_waitcnt vmcnt(6)
	s_mov_b64 s[54:55], 0

.LBB0_1155:
	s_barrier
	v_mfma_f32_16x16x32_bf16 v[36:39], v[96:99], v[144:147], v[36:39]
	v_mfma_f32_16x16x32_bf16 v[32:35], v[104:107], v[144:147], v[32:35]
	v_mfma_f32_16x16x32_bf16 v[20:23], v[96:99], v[136:139], v[20:23]
	v_mfma_f32_16x16x32_bf16 v[16:19], v[104:107], v[136:139], v[16:19]
	v_mfma_f32_16x16x32_bf16 v[4:7], v[96:99], v[128:131], v[4:7]
	v_mfma_f32_16x16x32_bf16 v[0:3], v[104:107], v[128:131], v[0:3]
	v_mfma_f32_16x16x32_bf16 v[36:39], v[100:103], v[148:151], v[36:39]
	v_mfma_f32_16x16x32_bf16 v[32:35], v[108:111], v[148:151], v[32:35]
	v_mfma_f32_16x16x32_bf16 v[20:23], v[100:103], v[140:143], v[20:23]
	v_mfma_f32_16x16x32_bf16 v[16:19], v[108:111], v[140:143], v[16:19]
	v_mfma_f32_16x16x32_bf16 v[4:7], v[100:103], v[132:135], v[4:7]
	v_mfma_f32_16x16x32_bf16 v[0:3], v[108:111], v[132:135], v[0:3]
	s_add_i32 s71, s71, 2
	s_add_u32 s28, s28, 0x100
	s_addc_u32 s29, s29, 0
	s_cmpk_gt_u32 s71, 0x55
	s_barrier
	s_cbranch_scc1 .LBB0_1172

.LBB0_1158:
	s_add_u32 s4, s4, 0x100
	s_addc_u32 s5, s5, 0
	s_waitcnt lgkmcnt(8)
	s_barrier
	s_waitcnt lgkmcnt(0)
	s_cmpk_eq_i32 s71, 0x54
	s_cselect_b32 s37, s25, s5
	s_cselect_b32 s36, s24, s4
	s_cselect_b32 s31, s7, s29
	s_cselect_b32 s30, s6, s28
	s_waitcnt lgkmcnt(0)
	v_mfma_f32_16x16x32_bf16 v[92:95], v[96:99], v[144:147], v[92:95]
	v_mfma_f32_16x16x32_bf16 v[88:91], v[104:107], v[144:147], v[88:91]
	v_mfma_f32_16x16x32_bf16 v[76:79], v[96:99], v[136:139], v[76:79]
	v_mfma_f32_16x16x32_bf16 v[72:75], v[104:107], v[136:139], v[72:75]
	v_mfma_f32_16x16x32_bf16 v[60:63], v[96:99], v[128:131], v[60:63]
	v_mfma_f32_16x16x32_bf16 v[56:59], v[104:107], v[128:131], v[56:59]
	v_mfma_f32_16x16x32_bf16 v[92:95], v[100:103], v[148:151], v[92:95]
	v_mfma_f32_16x16x32_bf16 v[88:91], v[108:111], v[148:151], v[88:91]
	v_mfma_f32_16x16x32_bf16 v[76:79], v[100:103], v[140:143], v[76:79]
	v_mfma_f32_16x16x32_bf16 v[72:75], v[108:111], v[140:143], v[72:75]
	v_mfma_f32_16x16x32_bf16 v[60:63], v[100:103], v[132:135], v[60:63]
	v_mfma_f32_16x16x32_bf16 v[56:59], v[108:111], v[132:135], v[56:59]
	s_barrier
	s_mov_b32 m0, s46
	v_add_u32_e32 v124, 0x14000, v188
	v_lshl_add_u64 v[168:169], s[30:31], 0, v[152:153]
	ds_read_b128 v[112:115], v124
	ds_read_b128 v[116:119], v124 offset:1024
	ds_read_b128 v[120:123], v124 offset:2048
	ds_read_b128 v[124:127], v124 offset:3072
	global_load_lds_dwordx4 v[168:169], off
	v_lshl_add_u64 v[170:171], s[30:31], 0, v[154:155]
	s_mov_b32 m0, s47
	s_nop 0
	global_load_lds_dwordx4 v[170:171], off
	s_barrier
	s_waitcnt lgkmcnt(0)
	s_waitcnt lgkmcnt(0)
	v_mfma_f32_16x16x32_bf16 v[84:87], v[112:115], v[144:147], v[84:87]
	v_mfma_f32_16x16x32_bf16 v[80:83], v[120:123], v[144:147], v[80:83]
	v_mfma_f32_16x16x32_bf16 v[68:71], v[112:115], v[136:139], v[68:71]
	v_mfma_f32_16x16x32_bf16 v[64:67], v[120:123], v[136:139], v[64:67]
	v_mfma_f32_16x16x32_bf16 v[52:55], v[112:115], v[128:131], v[52:55]
	v_mfma_f32_16x16x32_bf16 v[48:51], v[120:123], v[128:131], v[48:51]
	v_mfma_f32_16x16x32_bf16 v[84:87], v[116:119], v[148:151], v[84:87]
	v_mfma_f32_16x16x32_bf16 v[80:83], v[124:127], v[148:151], v[80:83]
	v_mfma_f32_16x16x32_bf16 v[68:71], v[116:119], v[140:143], v[68:71]
	v_mfma_f32_16x16x32_bf16 v[64:67], v[124:127], v[140:143], v[64:67]
	v_mfma_f32_16x16x32_bf16 v[52:55], v[116:119], v[132:135], v[52:55]
	v_mfma_f32_16x16x32_bf16 v[48:51], v[124:127], v[132:135], v[48:51]
	s_mov_b32 m0, s43
	v_lshl_add_u64 v[172:173], s[36:37], 0, v[152:153]
	s_barrier
	ds_read_b128 v[144:147], v190 offset:16384
	ds_read_b128 v[148:151], v190 offset:17408
	ds_read_b128 v[136:139], v190 offset:18432
	ds_read_b128 v[140:143], v190 offset:19456
	ds_read_b128 v[128:131], v190 offset:20480
	ds_read_b128 v[132:135], v190 offset:21504
	global_load_lds_dwordx4 v[172:173], off
	s_and_b64 vcc, exec, s[2:3]
	v_lshl_add_u64 v[166:167], s[36:37], 0, v[154:155]
	s_cbranch_vccnz .LBB0_1160
	s_add_i32 m0, s43, 0x2000
	s_nop 0
	global_load_lds_dwordx4 v[166:167], off
.LBB0_1160:
	s_barrier
	s_waitcnt lgkmcnt(0)
	s_waitcnt lgkmcnt(0)
	v_mfma_f32_16x16x32_bf16 v[44:47], v[96:99], v[144:147], v[44:47]
	v_mfma_f32_16x16x32_bf16 v[40:43], v[104:107], v[144:147], v[40:43]
	v_mfma_f32_16x16x32_bf16 v[28:31], v[96:99], v[136:139], v[28:31]
	v_mfma_f32_16x16x32_bf16 v[24:27], v[104:107], v[136:139], v[24:27]
	v_mfma_f32_16x16x32_bf16 v[12:15], v[96:99], v[128:131], v[12:15]
	v_mfma_f32_16x16x32_bf16 v[8:11], v[104:107], v[128:131], v[8:11]
	v_mfma_f32_16x16x32_bf16 v[44:47], v[100:103], v[148:151], v[44:47]
	v_mfma_f32_16x16x32_bf16 v[40:43], v[108:111], v[148:151], v[40:43]
	v_mfma_f32_16x16x32_bf16 v[28:31], v[100:103], v[140:143], v[28:31]
	v_mfma_f32_16x16x32_bf16 v[24:27], v[108:111], v[140:143], v[24:27]
	v_mfma_f32_16x16x32_bf16 v[12:15], v[100:103], v[132:135], v[12:15]
	v_mfma_f32_16x16x32_bf16 v[8:11], v[108:111], v[132:135], v[8:11]
	s_barrier
	s_add_u32 s34, s30, 0x160000
	s_addc_u32 s35, s31, 0
	s_mov_b32 m0, s48
	v_lshl_add_u64 v[96:97], s[34:35], 0, v[152:153]
	global_load_lds_dwordx4 v[96:97], off
	v_lshl_add_u64 v[96:97], s[34:35], 0, v[154:155]
	s_mov_b32 m0, s49
	s_mov_b64 s[38:39], -1
	global_load_lds_dwordx4 v[96:97], off
	s_and_b64 vcc, exec, s[8:9]
	s_cbranch_vccz .LBB0_1162
	s_waitcnt vmcnt(6)
	s_mov_b64 s[38:39], 0

.LBB0_1164:
	s_barrier
	v_mfma_f32_16x16x32_bf16 v[36:39], v[112:115], v[144:147], v[36:39]
	v_mfma_f32_16x16x32_bf16 v[32:35], v[120:123], v[144:147], v[32:35]
	v_mfma_f32_16x16x32_bf16 v[20:23], v[112:115], v[136:139], v[20:23]
	v_mfma_f32_16x16x32_bf16 v[16:19], v[120:123], v[136:139], v[16:19]
	v_mfma_f32_16x16x32_bf16 v[4:7], v[112:115], v[128:131], v[4:7]
	v_mfma_f32_16x16x32_bf16 v[0:3], v[120:123], v[128:131], v[0:3]
	v_mfma_f32_16x16x32_bf16 v[36:39], v[116:119], v[148:151], v[36:39]
	v_mfma_f32_16x16x32_bf16 v[32:35], v[124:127], v[148:151], v[32:35]
	v_mfma_f32_16x16x32_bf16 v[20:23], v[116:119], v[140:143], v[20:23]
	v_mfma_f32_16x16x32_bf16 v[16:19], v[124:127], v[140:143], v[16:19]
	v_mfma_f32_16x16x32_bf16 v[4:7], v[116:119], v[132:135], v[4:7]
	v_mfma_f32_16x16x32_bf16 v[0:3], v[124:127], v[132:135], v[0:3]
	v_add_u32_e32 v96, 0x18000, v188
	s_barrier
	ds_read_b128 v[112:115], v96
	ds_read_b128 v[116:119], v96 offset:1024
	ds_read_b128 v[120:123], v96 offset:2048
	ds_read_b128 v[124:127], v96 offset:3072
	s_add_u32 s36, s36, 0x108000
	s_addc_u32 s37, s37, 0
	s_mov_b32 m0, s50
	v_lshl_add_u64 v[96:97], s[36:37], 0, v[152:153]
	ds_read_b128 v[144:147], v190 offset:32768
	ds_read_b128 v[148:151], v190 offset:33792
	ds_read_b128 v[136:139], v190 offset:34816
	ds_read_b128 v[140:143], v190 offset:35840
	ds_read_b128 v[128:131], v190 offset:36864
	ds_read_b128 v[132:135], v190 offset:37888
	global_load_lds_dwordx4 v[96:97], off
	s_and_b64 vcc, exec, s[2:3]
	s_cbranch_vccnz .LBB0_1166
	v_lshl_add_u64 v[96:97], s[36:37], 0, v[154:155]
	s_add_i32 m0, s43, 0x6000
	s_nop 0
	global_load_lds_dwordx4 v[96:97], off
.LBB0_1166:
	s_waitcnt lgkmcnt(8)
	s_barrier
	s_waitcnt lgkmcnt(0)
	s_waitcnt lgkmcnt(0)
	v_mfma_f32_16x16x32_bf16 v[92:95], v[112:115], v[144:147], v[92:95]
	v_mfma_f32_16x16x32_bf16 v[88:91], v[120:123], v[144:147], v[88:91]
	v_mfma_f32_16x16x32_bf16 v[76:79], v[112:115], v[136:139], v[76:79]
	v_mfma_f32_16x16x32_bf16 v[72:75], v[120:123], v[136:139], v[72:75]
	v_mfma_f32_16x16x32_bf16 v[60:63], v[112:115], v[128:131], v[60:63]
	v_mfma_f32_16x16x32_bf16 v[56:59], v[120:123], v[128:131], v[56:59]
	v_mfma_f32_16x16x32_bf16 v[92:95], v[116:119], v[148:151], v[92:95]
	v_mfma_f32_16x16x32_bf16 v[88:91], v[124:127], v[148:151], v[88:91]
	v_mfma_f32_16x16x32_bf16 v[76:79], v[116:119], v[140:143], v[76:79]
	v_mfma_f32_16x16x32_bf16 v[72:75], v[124:127], v[140:143], v[72:75]
	v_mfma_f32_16x16x32_bf16 v[60:63], v[116:119], v[132:135], v[60:63]
	v_mfma_f32_16x16x32_bf16 v[56:59], v[124:127], v[132:135], v[56:59]
	s_barrier
	s_mov_b32 m0, s51
	v_add_u32_e32 v108, 0x1c000, v188
	v_lshl_add_u64 v[168:169], v[168:169], 0, s[20:21]
	ds_read_b128 v[96:99], v108
	ds_read_b128 v[100:103], v108 offset:1024
	ds_read_b128 v[104:107], v108 offset:2048
	ds_read_b128 v[108:111], v108 offset:3072
	global_load_lds_dwordx4 v[168:169], off
	v_lshl_add_u64 v[168:169], v[170:171], 0, s[20:21]
	s_mov_b32 m0, s52
	s_nop 0
	global_load_lds_dwordx4 v[168:169], off
	s_barrier
	s_waitcnt lgkmcnt(0)
	s_waitcnt lgkmcnt(0)
	v_mfma_f32_16x16x32_bf16 v[84:87], v[96:99], v[144:147], v[84:87]
	v_mfma_f32_16x16x32_bf16 v[80:83], v[104:107], v[144:147], v[80:83]
	v_mfma_f32_16x16x32_bf16 v[68:71], v[96:99], v[136:139], v[68:71]
	v_mfma_f32_16x16x32_bf16 v[64:67], v[104:107], v[136:139], v[64:67]
	v_mfma_f32_16x16x32_bf16 v[52:55], v[96:99], v[128:131], v[52:55]
	v_mfma_f32_16x16x32_bf16 v[48:51], v[104:107], v[128:131], v[48:51]
	v_mfma_f32_16x16x32_bf16 v[84:87], v[100:103], v[148:151], v[84:87]
	v_mfma_f32_16x16x32_bf16 v[80:83], v[108:111], v[148:151], v[80:83]
	v_mfma_f32_16x16x32_bf16 v[68:71], v[100:103], v[140:143], v[68:71]
	v_mfma_f32_16x16x32_bf16 v[64:67], v[108:111], v[140:143], v[64:67]
	v_mfma_f32_16x16x32_bf16 v[52:55], v[100:103], v[132:135], v[52:55]
	v_mfma_f32_16x16x32_bf16 v[48:51], v[108:111], v[132:135], v[48:51]
	s_mov_b32 m0, s53
	v_lshl_add_u64 v[168:169], v[172:173], 0, s[20:21]
	s_barrier
	ds_read_b128 v[144:147], v190 offset:49152
	ds_read_b128 v[148:151], v190 offset:50176
	ds_read_b128 v[136:139], v190 offset:51200
	ds_read_b128 v[140:143], v190 offset:52224
	ds_read_b128 v[128:131], v190 offset:53248
	ds_read_b128 v[132:135], v190 offset:54272
	global_load_lds_dwordx4 v[168:169], off
	s_and_b64 vcc, exec, s[2:3]
	s_cbranch_vccnz .LBB0_1168
	v_lshl_add_u64 v[166:167], v[166:167], 0, s[20:21]
	s_add_i32 m0, s43, 0xa000
	s_nop 0
	global_load_lds_dwordx4 v[166:167], off
.LBB0_1168:
	s_barrier
	s_waitcnt lgkmcnt(0)
	s_waitcnt lgkmcnt(0)
	v_mfma_f32_16x16x32_bf16 v[44:47], v[112:115], v[144:147], v[44:47]
	v_mfma_f32_16x16x32_bf16 v[40:43], v[120:123], v[144:147], v[40:43]
	v_mfma_f32_16x16x32_bf16 v[28:31], v[112:115], v[136:139], v[28:31]
	v_mfma_f32_16x16x32_bf16 v[24:27], v[120:123], v[136:139], v[24:27]
	v_mfma_f32_16x16x32_bf16 v[12:15], v[112:115], v[128:131], v[12:15]
	v_mfma_f32_16x16x32_bf16 v[8:11], v[120:123], v[128:131], v[8:11]
	v_mfma_f32_16x16x32_bf16 v[44:47], v[116:119], v[148:151], v[44:47]
	v_mfma_f32_16x16x32_bf16 v[40:43], v[124:127], v[148:151], v[40:43]
	v_mfma_f32_16x16x32_bf16 v[28:31], v[116:119], v[140:143], v[28:31]
	v_mfma_f32_16x16x32_bf16 v[24:27], v[124:127], v[140:143], v[24:27]
	v_mfma_f32_16x16x32_bf16 v[12:15], v[116:119], v[132:135], v[12:15]
	v_mfma_f32_16x16x32_bf16 v[8:11], v[124:127], v[132:135], v[8:11]
	s_barrier
	s_add_u32 s30, s30, 0x160080
	s_addc_u32 s31, s31, 0
	s_mov_b32 m0, s54
	v_lshl_add_u64 v[112:113], s[30:31], 0, v[152:153]
	global_load_lds_dwordx4 v[112:113], off
	v_lshl_add_u64 v[112:113], s[30:31], 0, v[154:155]
	s_mov_b32 m0, s55
	s_mov_b64 s[30:31], -1
	global_load_lds_dwordx4 v[112:113], off
	s_and_b64 vcc, exec, s[8:9]
	s_cbranch_vccz .LBB0_1170
	s_waitcnt vmcnt(6)
	s_mov_b64 s[30:31], 0
